# P1 column-tile rotation 10 -> 20
# speedup vs baseline: 1.0112x; 1.0112x over previous
.LBB0_103:
	s_cmp_lt_i32 s82, 2
	s_cselect_b64 s[4:5], -1, 0
	s_add_u32 s6, s80, 0x1100000
	v_writelane_b32 v255, s84, 25
	s_addc_u32 s7, s81, 0
	v_writelane_b32 v255, s6, 26
	s_nop 1
	v_writelane_b32 v255, s7, 27
	s_add_u32 s6, s80, 0x1300000
	s_addc_u32 s7, s81, 0
	v_writelane_b32 v255, s6, 28
	s_nop 1
	v_writelane_b32 v255, s7, 29
	s_add_u32 s6, s80, 0x1b00000
	s_addc_u32 s7, s81, 0
	s_add_u32 s69, s80, 0x2600000
	v_writelane_b32 v255, s6, 30
	s_addc_u32 s70, s81, 0
	s_nop 0
	v_writelane_b32 v255, s7, 31
	s_add_u32 s6, s80, 0x2c00000
	s_addc_u32 s7, s81, 0
	s_add_u32 s60, s80, 0x8c00000
	s_addc_u32 s61, s81, 0
	s_add_u32 s96, s80, 0xdc00000
	s_addc_u32 s91, s81, 0
	s_add_u32 s62, s80, 0x7c00000
	v_writelane_b32 v255, s6, 32
	s_addc_u32 s63, s81, 0
	s_and_b64 s[28:29], s[4:5], s[0:1]
	v_writelane_b32 v255, s7, 33
	s_andn2_b64 vcc, exec, s[28:29]
	s_cbranch_vccnz .LBB0_220
	s_cmpk_lt_i32 s2, 0x590
	s_cselect_b64 s[4:5], -1, 0
	s_cmpk_gt_i32 s2, 0x58f
	v_readfirstlane_b32 s6, v216
	s_cbranch_scc1 .LBB0_107
	s_cmpk_gt_i32 s2, 0x57f
	s_cbranch_scc1 .LBB0_108
	s_ashr_i32 s0, s2, 31
	s_lshr_b32 s0, s0, 29
	s_add_i32 s0, s2, s0
	s_ashr_i32 s1, s0, 3
	s_and_b32 s0, s0, -8
	s_sub_i32 s0, s2, s0
	s_cmp_lt_i32 s0, 0
	s_movk_i32 s7, 0xb1
	s_cselect_b32 s7, s7, 0xb0
	s_mul_i32 s0, s0, s7
	s_add_i32 s0, s0, s1
	s_mul_hi_i32 s1, s0, 0x2e8ba2e9
	s_lshr_b32 s7, s1, 31
	s_ashr_i32 s1, s1, 5
	s_add_i32 s1, s1, s7
	s_lshl_b32 s7, s1, 3
	s_mulk_i32 s1, 0xb0
	s_sub_i32 s0, s0, s1
	s_sext_i32_i16 s1, s0
	s_bfe_u32 s1, s1, 0x3001c
	s_add_i32 s1, s0, s1
	s_bfe_u32 s8, s1, 0xd0003
	s_and_b32 s1, s1, 0xfff8
	s_sub_i32 s0, s0, s1
	s_sext_i32_i16 s0, s0
	s_add_i32 s8, s8, 20
	s_add_i32 s38, s7, s0
	s_bfe_i32 s0, s8, 0x80000
	s_mul_i32 s0, s0, 0xffbb
	s_bfe_u32 s0, s0, 0x80008
	s_add_i32 s0, s0, s8
	s_bfe_i32 s1, s0, 0x80000
	s_and_b32 s1, 0xffff, s1
	s_lshr_b32 s1, s1, 4
	s_bfe_u32 s0, s0, 0x10007
	s_add_i32 s0, s1, s0
	s_mul_i32 s0, s0, 22
	s_sub_i32 s0, s8, s0
	s_mov_b32 s59, 0
	s_sext_i32_i8 s90, s0
	s_mov_b64 s[0:1], -1
	s_andn2_b64 vcc, exec, s[4:5]
	v_lshlrev_b32_e32 v16, 2, v216
	s_cbranch_vccz .LBB0_109
	s_branch .LBB0_178

.LBB0_117:
	s_andn2_b64 vcc, exec, s[12:13]
	s_mov_b32 s69, 1
	s_cbranch_vccnz .LBB0_119
	s_ashr_i32 s5, s4, 31
	s_lshr_b32 s5, s5, 29
	s_add_i32 s5, s4, s5
	s_ashr_i32 s12, s5, 3
	s_and_b32 s5, s5, -8
	s_sub_i32 s4, s4, s5
	s_cmp_lt_i32 s4, 0
	s_movk_i32 s5, 0xb1
	s_cselect_b32 s5, s5, 0xb0
	s_mul_i32 s4, s4, s5
	s_add_i32 s4, s4, s12
	s_mul_hi_i32 s5, s4, 0x2e8ba2e9
	s_lshr_b32 s12, s5, 31
	s_ashr_i32 s5, s5, 5
	s_add_i32 s5, s5, s12
	s_lshl_b32 s12, s5, 3
	s_sub_i32 s13, 64, s12
	s_min_i32 s13, s13, 8
	s_abs_i32 s14, s13
	v_cvt_f32_u32_e32 v0, s14
	s_sub_i32 s16, 0, s14
	s_mulk_i32 s5, 0xb0
	s_sub_i32 s4, s4, s5
	v_rcp_iflag_f32_e32 v0, v0
	s_abs_i32 s5, s4
	s_xor_b32 s15, s4, s13
	s_ashr_i32 s15, s15, 31
	v_mul_f32_e32 v0, 0x4f7ffffe, v0
	v_cvt_u32_f32_e32 v0, v0
	s_mov_b32 s69, 0
	v_readfirstlane_b32 s17, v0
	s_mul_i32 s16, s16, s17
	s_mul_hi_u32 s16, s17, s16
	s_add_i32 s17, s17, s16
	s_mul_hi_u32 s16, s5, s17
	s_mul_i32 s17, s16, s14
	s_sub_i32 s5, s5, s17
	s_add_i32 s17, s16, 1
	s_sub_i32 s18, s5, s14
	s_cmp_ge_u32 s5, s14
	s_cselect_b32 s16, s17, s16
	s_cselect_b32 s5, s18, s5
	s_add_i32 s17, s16, 1
	s_cmp_ge_u32 s5, s14
	s_cselect_b32 s5, s17, s16
	s_xor_b32 s5, s5, s15
	s_sub_i32 s5, s5, s15
	s_mul_i32 s13, s5, s13
	s_sub_i32 s4, s4, s13
	s_add_i32 s5, s5, 20
	s_add_i32 s42, s12, s4
	s_sext_i32_i16 s4, s5
	s_mulk_i32 s4, 0xba3
	s_lshr_b32 s12, s4, 31
	s_lshr_b32 s4, s4, 16
	s_add_i32 s4, s4, s12
	s_mul_i32 s4, s4, 22
	s_sub_i32 s4, s5, s4
	s_sext_i32_i16 s44, s4
